# grid barrier: waiters poll the cross-XCD arrival counter directly (monotone threshold) instead of the separate generation word
# speedup vs baseline: 1.0053x; 1.0053x over previous
.LBB0_70:
	s_mov_b64 s[4:5], exec
	v_readlane_b32 s6, v250, 4
	v_readlane_b32 s7, v250, 5
	s_and_b64 s[6:7], s[4:5], s[6:7]
	s_mov_b64 exec, s[6:7]
	s_cbranch_execz .LBB0_85
	s_add_i32 s3, 0, 0x22fc8
	s_waitcnt lgkmcnt(0)
	v_mov_b32_e32 v0, s3
	v_mov_b32_e32 v1, 0x17000
	ds_read_b32 v0, v0
	v_mov_b32_e32 v2, 0x22fc4
	ds_read_b32 v2, v2
	global_load_dword v1, v1, s[68:69] offset:1024 sc1
	s_add_u32 s8, s68, 0x17500
	s_addc_u32 s9, s69, 0
	s_waitcnt vmcnt(0) lgkmcnt(0)
	v_add_u32_e32 v0, 1, v0
	v_mul_lo_u32 v0, v0, v2
	v_cmp_ge_u32_e32 vcc, v1, v0
	s_cbranch_vccnz .LBB0_84
	s_add_u32 s6, s68, 0x14200
	s_addc_u32 s7, s69, 0
	s_mov_b32 s3, 1
	v_mov_b32_e32 v1, 0
	s_branch .LBB0_74

.LBB0_76:
	global_load_dword v2, v1, s[8:9] offset:-256 sc1
	s_add_i32 s3, s3, 1
	s_mov_b64 s[12:13], -1
	s_waitcnt vmcnt(0)
	v_cmp_ge_u32_e64 s[10:11], v2, v0
	s_branch .LBB0_73

.LBB0_134:
	s_mov_b64 s[0:1], exec
	v_readlane_b32 s4, v250, 4
	v_readlane_b32 s5, v250, 5
	s_and_b64 s[4:5], s[0:1], s[4:5]
	s_mov_b64 exec, s[4:5]
	s_cbranch_execz .LBB0_149
	s_add_i32 s3, 0, 0x22fc8
	s_waitcnt lgkmcnt(1)
	v_mov_b32_e32 v0, s3
	v_mov_b32_e32 v1, 0x17000
	ds_read_b32 v0, v0
	v_mov_b32_e32 v2, 0x22fc4
	ds_read_b32 v2, v2
	global_load_dword v1, v1, s[68:69] offset:1024 sc1
	s_add_u32 s6, s68, 0x17500
	s_addc_u32 s7, s69, 0
	s_waitcnt vmcnt(0) lgkmcnt(0)
	v_add_u32_e32 v0, 1, v0
	v_mul_lo_u32 v0, v0, v2
	v_cmp_ge_u32_e32 vcc, v1, v0
	s_cbranch_vccnz .LBB0_148
	s_add_u32 s4, s68, 0x14200
	s_addc_u32 s5, s69, 0
	s_mov_b32 s3, 1
	v_mov_b32_e32 v1, 0
	s_branch .LBB0_138

.LBB0_140:
	global_load_dword v2, v1, s[6:7] offset:-256 sc1
	s_add_i32 s3, s3, 1
	s_mov_b64 s[10:11], -1
	s_waitcnt vmcnt(0)
	v_cmp_ge_u32_e64 s[8:9], v2, v0
	s_branch .LBB0_137

.LBB0_781:
	s_mov_b64 s[4:5], exec
	v_readlane_b32 s6, v250, 4
	v_readlane_b32 s7, v250, 5
	s_and_b64 s[6:7], s[4:5], s[6:7]
	s_mov_b64 exec, s[6:7]
	s_cbranch_execz .LBB0_796
	s_add_i32 s3, 0, 0x22fc8
	v_mov_b32_e32 v0, s3
	v_mov_b32_e32 v1, 0x17000
	ds_read_b32 v0, v0
	v_mov_b32_e32 v2, 0x22fc4
	ds_read_b32 v2, v2
	global_load_dword v1, v1, s[68:69] offset:1024 sc1
	s_add_u32 s8, s68, 0x17500
	s_addc_u32 s9, s69, 0
	s_waitcnt vmcnt(0) lgkmcnt(0)
	v_add_u32_e32 v0, 1, v0
	v_mul_lo_u32 v0, v0, v2
	v_cmp_ge_u32_e32 vcc, v1, v0
	s_cbranch_vccnz .LBB0_795
	s_add_u32 s6, s68, 0x14200
	s_addc_u32 s7, s69, 0
	s_mov_b32 s3, 1
	v_mov_b32_e32 v1, 0
	s_branch .LBB0_785

.LBB0_933:
	s_mov_b64 s[0:1], exec
	v_readlane_b32 s2, v250, 4
	v_readlane_b32 s3, v250, 5
	v_readlane_b32 s94, v250, 48
	v_readlane_b32 s40, v250, 54
	s_and_b64 s[2:3], s[0:1], s[2:3]
	v_readlane_b32 s95, v250, 49
	v_readlane_b32 s41, v250, 55
	s_mov_b64 exec, s[2:3]
	s_cbranch_execz .LBB0_948
	s_add_i32 s2, 0, 0x22fc8
	s_waitcnt lgkmcnt(1)
	v_mov_b32_e32 v0, s2
	v_mov_b32_e32 v1, 0x17000
	ds_read_b32 v0, v0
	v_mov_b32_e32 v2, 0x22fc4
	ds_read_b32 v2, v2
	global_load_dword v1, v1, s[68:69] offset:1024 sc1
	s_add_u32 s8, s68, 0x17500
	s_addc_u32 s9, s69, 0
	s_waitcnt vmcnt(0) lgkmcnt(0)
	v_add_u32_e32 v0, 1, v0
	v_mul_lo_u32 v0, v0, v2
	v_cmp_ge_u32_e32 vcc, v1, v0
	s_cbranch_vccnz .LBB0_947
	s_add_u32 s4, s68, 0x14200
	s_addc_u32 s5, s69, 0
	s_mov_b32 s2, 1
	v_mov_b32_e32 v1, 0
	s_branch .LBB0_937

.LBB0_939:
	global_load_dword v2, v1, s[8:9] offset:-256 sc1
	s_add_i32 s2, s2, 1
	s_mov_b64 s[12:13], -1
	s_waitcnt vmcnt(0)
	v_cmp_ge_u32_e64 s[10:11], v2, v0
	s_branch .LBB0_936

.LBB0_1002:
	s_mov_b64 s[0:1], exec
	v_readlane_b32 s2, v250, 4
	v_readlane_b32 s3, v250, 5
	s_and_b64 s[2:3], s[0:1], s[2:3]
	s_mov_b64 exec, s[2:3]
	s_cbranch_execz .LBB0_1017
	s_add_i32 s2, 0, 0x22fc8
	s_waitcnt lgkmcnt(1)
	v_mov_b32_e32 v0, s2
	v_mov_b32_e32 v1, 0x17000
	ds_read_b32 v0, v0
	v_mov_b32_e32 v2, 0x22fc4
	ds_read_b32 v2, v2
	global_load_dword v1, v1, s[68:69] offset:1024 sc1
	s_add_u32 s8, s68, 0x17500
	s_addc_u32 s9, s69, 0
	s_waitcnt vmcnt(0) lgkmcnt(0)
	v_add_u32_e32 v0, 1, v0
	v_mul_lo_u32 v0, v0, v2
	v_cmp_ge_u32_e32 vcc, v1, v0
	s_cbranch_vccnz .LBB0_1016
	s_add_u32 s4, s68, 0x14200
	s_addc_u32 s5, s69, 0
	s_mov_b32 s2, 1
	v_mov_b32_e32 v1, 0
	s_branch .LBB0_1006

.LBB0_1079:
	s_or_b64 exec, exec, s[10:11]
	v_cvt_f32_u32_e32 v4, v2
	s_waitcnt vmcnt(0)
	v_readfirstlane_b32 s2, v3
	v_sub_u32_e32 v3, 0, v2
	v_rcp_iflag_f32_e32 v4, v4
	v_add_u32_e32 v5, s2, v1
	v_mul_f32_e32 v4, 0x4f7ffffe, v4
	v_cvt_u32_f32_e32 v4, v4
	v_mul_lo_u32 v1, v3, v4
	v_mul_hi_u32 v1, v4, v1
	v_add_u32_e32 v1, v4, v1
	v_mul_hi_u32 v1, v5, v1
	v_mul_lo_u32 v3, v1, v2
	v_sub_u32_e32 v3, v5, v3
	v_add_u32_e32 v4, 1, v1
	v_cmp_ge_u32_e32 vcc, v3, v2
	s_nop 1
	v_cndmask_b32_e32 v1, v1, v4, vcc
	v_sub_u32_e32 v4, v3, v2
	v_cndmask_b32_e32 v3, v3, v4, vcc
	v_add_u32_e32 v4, 1, v1
	v_cmp_ge_u32_e32 vcc, v3, v2
	v_add_u32_e32 v3, 1, v5
	s_nop 0
	v_cndmask_b32_e32 v1, v1, v4, vcc
	v_mul_lo_u32 v4, v2, v1
	v_add_u32_e32 v2, v4, v2
	v_cmp_ne_u32_e32 vcc, v3, v2
	s_and_saveexec_b64 s[2:3], vcc
	s_xor_b64 s[10:11], exec, s[2:3]
	s_cbranch_execz .LBB0_1093
	s_waitcnt lgkmcnt(0)
	v_add_u32_e32 v1, 1, v1
	v_mul_lo_u32 v1, v1, v0
	v_mov_b32_e32 v0, 0x17000
	global_load_dword v0, v0, s[68:69] offset:1024 sc1
	s_add_u32 s18, s68, 0x17500
	s_addc_u32 s19, s69, 0
	s_waitcnt vmcnt(0)
	v_cmp_lt_u32_e32 vcc, v0, v1
	s_and_saveexec_b64 s[12:13], vcc
	s_cbranch_execz .LBB0_1092
	s_add_u32 s16, s68, 0x14200
	s_addc_u32 s17, s69, 0
	s_mov_b32 s2, 1
	s_mov_b64 s[20:21], 0
	v_mov_b32_e32 v0, 0
	s_branch .LBB0_1083

.LBB0_1085:
	global_load_dword v2, v0, s[18:19] offset:-256 sc1
	s_add_i32 s2, s2, 1
	s_mov_b64 s[26:27], -1
	s_waitcnt vmcnt(0)
	v_cmp_ge_u32_e32 vcc, v2, v1
	s_orn2_b64 s[24:25], vcc, exec
	s_branch .LBB0_1082

.LBB0_1096:
	s_or_b64 exec, exec, s[12:13]
	v_cvt_f32_u32_e32 v3, v0
	s_waitcnt vmcnt(0)
	v_readfirstlane_b32 s2, v2
	s_add_u32 s12, s68, 0x17500
	s_addc_u32 s13, s69, 0
	v_rcp_iflag_f32_e32 v3, v3
	v_add_u32_e32 v1, s2, v1
	v_add_u32_e32 v4, 1, v1
	s_mov_b64 s[16:17], -1
	v_mul_f32_e32 v2, 0x4f7ffffe, v3
	v_cvt_u32_f32_e32 v2, v2
	v_sub_u32_e32 v3, 0, v0
	v_mul_lo_u32 v3, v3, v2
	v_mul_hi_u32 v3, v2, v3
	v_add_u32_e32 v2, v2, v3
	v_mul_hi_u32 v2, v1, v2
	v_mul_lo_u32 v3, v2, v0
	v_sub_u32_e32 v1, v1, v3
	v_add_u32_e32 v5, 1, v2
	v_cmp_ge_u32_e32 vcc, v1, v0
	v_sub_u32_e32 v3, v1, v0
	s_nop 0
	v_cndmask_b32_e32 v2, v2, v5, vcc
	v_cndmask_b32_e32 v1, v1, v3, vcc
	v_add_u32_e32 v3, 1, v2
	v_cmp_ge_u32_e32 vcc, v1, v0
	s_nop 1
	v_cndmask_b32_e32 v2, v2, v3, vcc
	v_mul_lo_u32 v1, v0, v2
	v_add_u32_e32 v0, v1, v0
	v_cmp_ne_u32_e32 vcc, v4, v0
	v_mov_b32_e32 v2, v0
	v_mov_b64_e32 v[0:1], s[12:13]
	s_and_saveexec_b64 s[10:11], vcc
	s_cbranch_execz .LBB0_1108
	v_mov_b32_e32 v0, 0
	global_load_dword v1, v0, s[12:13] offset:-256 sc1
	s_mov_b64 s[20:21], 0
	s_waitcnt vmcnt(0)
	v_cmp_lt_u32_e32 vcc, v1, v2
	s_and_saveexec_b64 s[18:19], vcc
	s_cbranch_execz .LBB0_1107
	s_add_u32 s16, s68, 0x14200
	s_addc_u32 s17, s69, 0
	s_mov_b32 s2, 1
	s_branch .LBB0_1100

.LBB0_1102:
	global_load_dword v1, v0, s[12:13] offset:-256 sc1
	s_add_i32 s2, s2, 1
	s_mov_b64 s[24:25], -1
	s_waitcnt vmcnt(0)
	v_cmp_ge_u32_e32 vcc, v1, v2
	s_orn2_b64 s[28:29], vcc, exec
	s_branch .LBB0_1099

.LBB0_1148:
	s_or_b64 exec, exec, s[8:9]
	v_cvt_f32_u32_e32 v4, v2
	s_waitcnt vmcnt(0)
	v_readfirstlane_b32 s2, v3
	v_sub_u32_e32 v3, 0, v2
	v_rcp_iflag_f32_e32 v4, v4
	v_add_u32_e32 v5, s2, v1
	v_mul_f32_e32 v4, 0x4f7ffffe, v4
	v_cvt_u32_f32_e32 v4, v4
	v_mul_lo_u32 v1, v3, v4
	v_mul_hi_u32 v1, v4, v1
	v_add_u32_e32 v1, v4, v1
	v_mul_hi_u32 v1, v5, v1
	v_mul_lo_u32 v3, v1, v2
	v_sub_u32_e32 v3, v5, v3
	v_add_u32_e32 v4, 1, v1
	v_cmp_ge_u32_e32 vcc, v3, v2
	s_nop 1
	v_cndmask_b32_e32 v1, v1, v4, vcc
	v_sub_u32_e32 v4, v3, v2
	v_cndmask_b32_e32 v3, v3, v4, vcc
	v_add_u32_e32 v4, 1, v1
	v_cmp_ge_u32_e32 vcc, v3, v2
	v_add_u32_e32 v3, 1, v5
	s_nop 0
	v_cndmask_b32_e32 v1, v1, v4, vcc
	v_mul_lo_u32 v4, v2, v1
	v_add_u32_e32 v2, v4, v2
	v_cmp_ne_u32_e32 vcc, v3, v2
	s_and_saveexec_b64 s[2:3], vcc
	s_xor_b64 s[8:9], exec, s[2:3]
	s_cbranch_execz .LBB0_1162
	s_waitcnt lgkmcnt(0)
	v_add_u32_e32 v1, 1, v1
	v_mul_lo_u32 v1, v1, v0
	v_mov_b32_e32 v0, 0x17000
	global_load_dword v0, v0, s[68:69] offset:1024 sc1
	s_add_u32 s14, s68, 0x17500
	s_addc_u32 s15, s69, 0
	s_waitcnt vmcnt(0)
	v_cmp_lt_u32_e32 vcc, v0, v1
	s_and_saveexec_b64 s[10:11], vcc
	s_cbranch_execz .LBB0_1161
	s_add_u32 s12, s68, 0x14200
	s_addc_u32 s13, s69, 0
	s_mov_b32 s2, 1
	s_mov_b64 s[16:17], 0
	v_mov_b32_e32 v0, 0
	s_branch .LBB0_1152

.LBB0_1154:
	global_load_dword v2, v0, s[14:15] offset:-256 sc1
	s_add_i32 s2, s2, 1
	s_mov_b64 s[22:23], -1
	s_waitcnt vmcnt(0)
	v_cmp_ge_u32_e32 vcc, v2, v1
	s_orn2_b64 s[20:21], vcc, exec
	s_branch .LBB0_1151

.LBB0_1165:
	s_or_b64 exec, exec, s[10:11]
	v_cvt_f32_u32_e32 v3, v0
	s_waitcnt vmcnt(0)
	v_readfirstlane_b32 s2, v2
	s_add_u32 s10, s68, 0x17500
	s_addc_u32 s11, s69, 0
	v_rcp_iflag_f32_e32 v3, v3
	v_add_u32_e32 v1, s2, v1
	v_add_u32_e32 v4, 1, v1
	s_mov_b64 s[12:13], -1
	v_mul_f32_e32 v2, 0x4f7ffffe, v3
	v_cvt_u32_f32_e32 v2, v2
	v_sub_u32_e32 v3, 0, v0
	v_mul_lo_u32 v3, v3, v2
	v_mul_hi_u32 v3, v2, v3
	v_add_u32_e32 v2, v2, v3
	v_mul_hi_u32 v2, v1, v2
	v_mul_lo_u32 v3, v2, v0
	v_sub_u32_e32 v1, v1, v3
	v_add_u32_e32 v5, 1, v2
	v_cmp_ge_u32_e32 vcc, v1, v0
	v_sub_u32_e32 v3, v1, v0
	s_nop 0
	v_cndmask_b32_e32 v2, v2, v5, vcc
	v_cndmask_b32_e32 v1, v1, v3, vcc
	v_add_u32_e32 v3, 1, v2
	v_cmp_ge_u32_e32 vcc, v1, v0
	s_nop 1
	v_cndmask_b32_e32 v2, v2, v3, vcc
	v_mul_lo_u32 v1, v0, v2
	v_add_u32_e32 v0, v1, v0
	v_cmp_ne_u32_e32 vcc, v4, v0
	v_mov_b32_e32 v2, v0
	v_mov_b64_e32 v[0:1], s[10:11]
	s_and_saveexec_b64 s[8:9], vcc
	s_cbranch_execz .LBB0_1177
	v_mov_b32_e32 v0, 0
	global_load_dword v1, v0, s[10:11] offset:-256 sc1
	s_mov_b64 s[16:17], 0
	s_waitcnt vmcnt(0)
	v_cmp_lt_u32_e32 vcc, v1, v2
	s_and_saveexec_b64 s[14:15], vcc
	s_cbranch_execz .LBB0_1176
	s_add_u32 s12, s68, 0x14200
	s_addc_u32 s13, s69, 0
	s_mov_b32 s2, 1
	s_branch .LBB0_1169

.LBB0_1171:
	global_load_dword v1, v0, s[10:11] offset:-256 sc1
	s_add_i32 s2, s2, 1
	s_mov_b64 s[20:21], -1
	s_waitcnt vmcnt(0)
	v_cmp_ge_u32_e32 vcc, v1, v2
	s_orn2_b64 s[24:25], vcc, exec
	s_branch .LBB0_1168
